# all serialized LDS bpermute reduction chains on executed paths replaced by DPP (retention-out, spatial LayerNorm stats, norm loop, q-epilogue rope exchange) on top of the v_rsf recipe
# speedup vs baseline: 1.0096x; 1.0042x over previous
.LBB0_135:
	s_waitcnt vmcnt(0) lgkmcnt(0)
	v_mov_b32_e32 v1, v139
	s_waitcnt lgkmcnt(0)
	v_mov_b32_e32 v0, v139
	s_add_i32 s0, s43, 0xffffe000
	v_lshrrev_b32_e32 v0, 4, v0
	v_and_b32_e32 v0, 12, v0
	s_lshr_b32 s0, s0, 12
	v_add_u32_e32 v0, s43, v0
	s_add_i32 s0, s0, 1
	v_lshlrev_b32_e32 v1, 2, v1
	v_cmp_lt_i32_e32 vcc, s8, v0
	v_mov_b32_e32 v2, s0
	v_and_b32_e32 v7, 0xfc, v1
	v_cndmask_b32_e32 v2, 0, v2, vcc
	v_lshlrev_b32_e32 v136, 1, v7
	v_ashrrev_i32_e32 v1, 31, v0
	v_add_u32_e32 v6, s9, v2
	v_lshl_add_u64 v[2:3], s[50:51], 0, v[136:137]
	v_lshlrev_b64 v[36:37], 11, v[0:1]
	v_lshl_add_u64 v[4:5], v[2:3], 0, v[36:37]
	global_load_dwordx2 v[38:39], v[4:5], off
	global_load_dwordx2 v[42:43], v[4:5], off offset:512
	global_load_dwordx2 v[46:47], v[4:5], off offset:1024
	global_load_dwordx2 v[50:51], v[4:5], off offset:1536
	v_add_u32_e32 v4, 1, v0
	v_ashrrev_i32_e32 v5, 31, v4
	v_lshlrev_b64 v[70:71], 11, v[4:5]
	v_lshl_add_u64 v[4:5], v[2:3], 0, v[70:71]
	global_load_dwordx2 v[58:59], v[4:5], off
	global_load_dwordx2 v[82:83], v[4:5], off offset:512
	global_load_dwordx2 v[78:79], v[4:5], off offset:1024
	global_load_dwordx2 v[88:89], v[4:5], off offset:1536
	v_add_u32_e32 v4, 2, v0
	v_add_u32_e32 v0, 3, v0
	v_ashrrev_i32_e32 v5, 31, v4
	v_ashrrev_i32_e32 v1, 31, v0
	v_lshlrev_b64 v[34:35], 11, v[4:5]
	v_lshlrev_b64 v[24:25], 11, v[0:1]
	v_lshl_add_u64 v[4:5], v[2:3], 0, v[34:35]
	v_lshl_add_u64 v[0:1], v[2:3], 0, v[24:25]
	global_load_dwordx2 v[32:33], v[4:5], off
	global_load_dwordx2 v[30:31], v[4:5], off offset:512
	global_load_dwordx2 v[28:29], v[4:5], off offset:1024
	global_load_dwordx2 v[26:27], v[4:5], off offset:1536
	global_load_dwordx2 v[22:23], v[0:1], off
	global_load_dwordx2 v[20:21], v[0:1], off offset:512
	global_load_dwordx2 v[18:19], v[0:1], off offset:1024
	global_load_dwordx2 v[16:17], v[0:1], off offset:1536
	v_mov_b64_e32 v[0:1], s[6:7]
	v_mad_i64_i32 v[0:1], s[0:1], v6, s33, v[0:1]
	s_mov_b64 s[0:1], 0x3000
	s_nop 0
	v_lshl_add_u64 v[12:13], v[0:1], 0, s[0:1]
	s_mov_b64 s[0:1], 0x4000
	v_lshl_add_u64 v[14:15], v[0:1], 0, s[0:1]
	v_lshlrev_b32_e32 v40, 2, v7
	v_mov_b32_e32 v41, v137
	v_lshl_add_u64 v[0:1], v[14:15], 0, v[40:41]
	global_load_dwordx4 v[66:69], v[0:1], off
	v_or_b32_e32 v4, 0x400, v40
	v_mov_b32_e32 v5, v137
	global_load_dwordx4 v[62:65], v40, s[40:41]
	v_lshl_add_u64 v[6:7], v[14:15], 0, v[4:5]
	global_load_dwordx4 v[84:87], v[6:7], off
	global_load_dwordx4 v[72:75], v4, s[40:41]
	v_or_b32_e32 v8, 0x800, v40
	v_mov_b32_e32 v9, v137
	v_lshl_add_u64 v[10:11], v[14:15], 0, v[8:9]
	global_load_dwordx4 v[100:103], v[10:11], off
	global_load_dwordx4 v[96:99], v8, s[40:41]
	v_lshl_add_u64 v[0:1], v[12:13], 0, v[40:41]
	v_or_b32_e32 v40, 0xc00, v40
	v_lshl_add_u64 v[14:15], v[14:15], 0, v[40:41]
	global_load_dwordx4 v[108:111], v[14:15], off
	global_load_dwordx4 v[104:107], v40, s[40:41]
	v_lshl_add_u64 v[4:5], v[12:13], 0, v[4:5]
	global_load_dwordx4 v[0:3], v[0:1], off
	v_lshl_add_u64 v[8:9], v[12:13], 0, v[8:9]
	global_load_dwordx4 v[4:7], v[4:5], off
	v_cmp_lt_i32_e32 vcc, v177, v176
	global_load_dwordx4 v[8:11], v[8:9], off
	v_lshl_add_u64 v[12:13], v[12:13], 0, v[40:41]
	v_cndmask_b32_e32 v40, v175, v177, vcc
	v_cmp_lt_i32_e32 vcc, v178, v176
	v_lshlrev_b32_e32 v90, 2, v40
	global_load_dwordx4 v[12:15], v[12:13], off
	v_cndmask_b32_e32 v40, v175, v178, vcc
	v_cmp_lt_i32_e32 vcc, v179, v176
	v_lshlrev_b32_e32 v91, 2, v40
	v_lshl_add_u64 v[44:45], s[30:31], 0, v[36:37]
	v_cndmask_b32_e32 v40, v175, v179, vcc
	v_cmp_lt_i32_e32 vcc, v180, v176
	v_lshlrev_b32_e32 v92, 2, v40
	v_lshl_add_u64 v[52:53], v[44:45], 0, v[136:137]
	v_cndmask_b32_e32 v40, v175, v180, vcc
	v_cmp_lt_i32_e32 vcc, v181, v176
	v_lshlrev_b32_e32 v93, 2, v40
	v_lshl_add_u64 v[70:71], s[30:31], 0, v[70:71]
	v_cndmask_b32_e32 v40, v175, v181, vcc
	v_lshlrev_b32_e32 v94, 2, v40
	v_xor_b32_e32 v40, 1, v175
	v_cmp_lt_i32_e32 vcc, v40, v176
	v_lshl_add_u64 v[34:35], s[30:31], 0, v[34:35]
	v_lshl_add_u64 v[24:25], s[30:31], 0, v[24:25]
	v_cndmask_b32_e32 v40, v175, v40, vcc
	v_lshlrev_b32_e32 v95, 2, v40
	s_add_i32 s42, s42, s5
	s_add_i32 s43, s43, s4
	s_cmpk_gt_i32 s42, 0x5ff
	s_waitcnt vmcnt(0)
	v_lshlrev_b32_e32 v54, 16, v39
	v_and_b32_e32 v55, 0xffff0000, v39
	v_lshlrev_b32_e32 v60, 16, v38
	v_and_b32_e32 v61, 0xffff0000, v38
	v_lshlrev_b32_e32 v56, 16, v43
	v_and_b32_e32 v57, 0xffff0000, v43
	v_mov_b32_e32 v44, v54
	v_mov_b32_e32 v45, v56
	v_mov_b32_e32 v48, v55
	v_mov_b32_e32 v49, v57
	v_pk_add_f32 v[38:39], v[66:67], 1.0 op_sel_hi:[1,0]
	v_pk_add_f32 v[36:37], v[68:69], 1.0 op_sel_hi:[1,0]
	v_mov_b32_e32 v66, v61
	v_pk_mul_f32 v[40:41], v[62:63], v[38:39]
	v_and_b32_e32 v63, 0xffff0000, v42
	v_lshlrev_b32_e32 v62, 16, v42
	v_pk_add_f32 v[42:43], v[84:85], 1.0 op_sel_hi:[1,0]
	v_mov_b32_e32 v67, v63
	v_pk_mul_f32 v[36:37], v[64:65], v[36:37]
	v_pk_mul_f32 v[42:43], v[72:73], v[42:43]
	v_mov_b32_e32 v64, v60
	v_mov_b32_e32 v65, v62
	v_pk_mul_f32 v[66:67], v[66:67], v[66:67]
	v_and_b32_e32 v69, 0xffff0000, v46
	v_and_b32_e32 v73, 0xffff0000, v50
	v_pk_fma_f32 v[64:65], v[64:65], v[64:65], v[66:67]
	v_lshlrev_b32_e32 v68, 16, v46
	v_lshlrev_b32_e32 v72, 16, v50
	v_mov_b32_e32 v84, v73
	v_mov_b32_e32 v85, v69
	v_pk_add_f32 v[38:39], v[86:87], 1.0 op_sel_hi:[1,0]
	v_pk_fma_f32 v[44:45], v[44:45], v[44:45], v[64:65]
	v_lshlrev_b32_e32 v64, 16, v47
	v_lshlrev_b32_e32 v66, 16, v51
	v_mov_b32_e32 v80, v72
	v_mov_b32_e32 v81, v68
	v_pk_mul_f32 v[84:85], v[84:85], v[84:85]
	v_pk_mul_f32 v[38:39], v[74:75], v[38:39]
	v_and_b32_e32 v65, 0xffff0000, v47
	v_and_b32_e32 v67, 0xffff0000, v51
	v_mov_b32_e32 v74, v66
	v_mov_b32_e32 v75, v64
	v_pk_fma_f32 v[80:81], v[80:81], v[80:81], v[84:85]
	v_pk_add_f32 v[46:47], v[100:101], 1.0 op_sel_hi:[1,0]
	v_mov_b32_e32 v76, v67
	v_mov_b32_e32 v77, v65
	v_pk_fma_f32 v[74:75], v[74:75], v[74:75], v[80:81]
	v_pk_fma_f32 v[112:113], v[48:49], v[48:49], v[44:45]
	v_pk_add_f32 v[44:45], v[102:103], 1.0 op_sel_hi:[1,0]
	v_pk_mul_f32 v[48:49], v[96:97], v[46:47]
	v_pk_fma_f32 v[96:97], v[76:77], v[76:77], v[74:75]
	v_and_b32_e32 v81, 0xffff0000, v58
	v_and_b32_e32 v77, 0xffff0000, v82
	v_pk_mul_f32 v[44:45], v[98:99], v[44:45]
	v_lshlrev_b32_e32 v80, 16, v58
	v_lshlrev_b32_e32 v76, 16, v82
	v_mov_b32_e32 v98, v81
	v_mov_b32_e32 v99, v77
	v_lshlrev_b32_e32 v74, 16, v59
	v_and_b32_e32 v75, 0xffff0000, v59
	v_lshl_add_u64 v[58:59], v[70:71], 0, v[136:137]
	v_lshlrev_b32_e32 v70, 16, v83
	v_mov_b32_e32 v86, v80
	v_mov_b32_e32 v87, v76
	v_pk_mul_f32 v[98:99], v[98:99], v[98:99]
	v_and_b32_e32 v71, 0xffff0000, v83
	v_mov_b32_e32 v82, v74
	v_mov_b32_e32 v83, v70
	v_pk_fma_f32 v[86:87], v[86:87], v[86:87], v[98:99]
	v_mov_b32_e32 v84, v75
	v_mov_b32_e32 v85, v71
	v_pk_fma_f32 v[82:83], v[82:83], v[82:83], v[86:87]
	v_pk_add_f32 v[50:51], v[108:109], 1.0 op_sel_hi:[1,0]
	v_pk_fma_f32 v[98:99], v[84:85], v[84:85], v[82:83]
	v_and_b32_e32 v87, 0xffff0000, v78
	v_and_b32_e32 v85, 0xffff0000, v88
	v_pk_mul_f32 v[50:51], v[104:105], v[50:51]
	v_lshlrev_b32_e32 v86, 16, v78
	v_lshlrev_b32_e32 v84, 16, v88
	v_mov_b32_e32 v104, v85
	v_mov_b32_e32 v105, v87
	v_lshlrev_b32_e32 v82, 16, v79
	v_lshlrev_b32_e32 v78, 16, v89
	v_mov_b32_e32 v102, v84
	v_mov_b32_e32 v103, v86
	v_pk_mul_f32 v[104:105], v[104:105], v[104:105]
	v_and_b32_e32 v83, 0xffff0000, v79
	v_and_b32_e32 v79, 0xffff0000, v89
	v_mov_b32_e32 v88, v78
	v_mov_b32_e32 v89, v82
	v_pk_fma_f32 v[102:103], v[102:103], v[102:103], v[104:105]
	v_mov_b32_e32 v100, v79
	v_mov_b32_e32 v101, v83
	v_pk_fma_f32 v[88:89], v[88:89], v[88:89], v[102:103]
	v_pk_add_f32 v[46:47], v[110:111], 1.0 op_sel_hi:[1,0]
	v_pk_fma_f32 v[88:89], v[100:101], v[100:101], v[88:89]
	v_mov_b32_e32 v100, v98
	v_mov_b32_e32 v101, v112
	v_mov_b32_e32 v112, v99
	v_pk_add_f32 v[98:99], v[100:101], v[112:113]
	v_mov_b32_e32 v100, v89
	v_mov_b32_e32 v101, v97
	v_pk_add_f32 v[98:99], v[100:101], v[98:99]
	v_mov_b32_e32 v89, v96
	v_pk_add_f32 v[88:89], v[88:89], v[98:99]
	v_pk_mul_f32 v[46:47], v[106:107], v[46:47]
	s_nop 1
	v_add_f32_dpp v88, v88, v88 row_ror:8 row_mask:0xf bank_mask:0xf
	v_add_f32_dpp v89, v89, v89 row_ror:8 row_mask:0xf bank_mask:0xf
	s_nop 0
	v_add_f32_dpp v88, v88, v88 row_ror:4 row_mask:0xf bank_mask:0xf
	v_add_f32_dpp v89, v89, v89 row_ror:4 row_mask:0xf bank_mask:0xf
	s_nop 0
	v_add_f32_dpp v88, v88, v88 row_ror:2 row_mask:0xf bank_mask:0xf
	v_add_f32_dpp v89, v89, v89 row_ror:2 row_mask:0xf bank_mask:0xf
	s_nop 0
	v_add_f32_dpp v88, v88, v88 row_ror:1 row_mask:0xf bank_mask:0xf
	v_add_f32_dpp v89, v89, v89 row_ror:1 row_mask:0xf bank_mask:0xf
	s_nop 0
	v_add_f32_dpp v88, v88, v88 row_bcast:15 row_mask:0xa bank_mask:0xf
	v_add_f32_dpp v89, v89, v89 row_bcast:15 row_mask:0xa bank_mask:0xf
	s_nop 0
	v_add_f32_dpp v88, v88, v88 row_bcast:31 row_mask:0xc bank_mask:0xf
	v_add_f32_dpp v89, v89, v89 row_bcast:31 row_mask:0xc bank_mask:0xf
	s_nop 0
	v_readlane_b32 s0, v88, 63
	v_readlane_b32 s1, v89, 63
	s_nop 1
	v_mov_b32_e32 v88, s0
	v_mov_b32_e32 v89, s1
	v_mov_b64_e32 v[96:97], s[10:11]
	v_pk_fma_f32 v[88:89], v[88:89], s[20:21], v[96:97] op_sel_hi:[1,0,0]
	s_nop 0
	v_mul_f32_e32 v98, 0x4b800000, v89
	v_cmp_gt_f32_e64 s[0:1], s36, v89
	v_cmp_gt_f32_e32 vcc, s36, v88
	s_nop 0
	v_cndmask_b32_e64 v89, v89, v98, s[0:1]
	v_rsq_f32_e32 v89, v89
	s_nop 0
	v_mul_f32_e32 v98, 0x45800000, v89
	v_cndmask_b32_e64 v98, v89, v98, s[0:1]
	v_pk_mul_f32 v[60:61], v[98:99], v[60:61] op_sel_hi:[0,1]
	v_pk_mul_f32 v[54:55], v[98:99], v[54:55] op_sel_hi:[0,1]
	v_pk_fma_f32 v[60:61], v[40:41], v[60:61], v[0:1]
	v_pk_fma_f32 v[54:55], v[36:37], v[54:55], v[2:3]
	v_cvt_pk_bf16_f32 v60, v60, v61
	v_cvt_pk_bf16_f32 v61, v54, v55
	v_pk_mul_f32 v[54:55], v[98:99], v[62:63] op_sel_hi:[0,1]
	v_pk_mul_f32 v[56:57], v[98:99], v[56:57] op_sel_hi:[0,1]
	v_pk_fma_f32 v[54:55], v[42:43], v[54:55], v[4:5]
	v_pk_fma_f32 v[56:57], v[38:39], v[56:57], v[6:7]
	v_cvt_pk_bf16_f32 v54, v54, v55
	v_cvt_pk_bf16_f32 v55, v56, v57
	global_store_dwordx2 v[52:53], v[54:55], off offset:512
	v_pk_mul_f32 v[54:55], v[98:99], v[68:69] op_sel_hi:[0,1]
	v_pk_mul_f32 v[56:57], v[98:99], v[64:65] op_sel_hi:[0,1]
	v_pk_fma_f32 v[54:55], v[48:49], v[54:55], v[8:9]
	v_pk_fma_f32 v[56:57], v[44:45], v[56:57], v[10:11]
	v_cvt_pk_bf16_f32 v54, v54, v55
	v_cvt_pk_bf16_f32 v55, v56, v57
	global_store_dwordx2 v[52:53], v[54:55], off offset:1024
	v_pk_mul_f32 v[54:55], v[98:99], v[72:73] op_sel_hi:[0,1]
	v_pk_mul_f32 v[56:57], v[98:99], v[66:67] op_sel_hi:[0,1]
	v_pk_fma_f32 v[54:55], v[50:51], v[54:55], v[12:13]
	v_pk_fma_f32 v[56:57], v[46:47], v[56:57], v[14:15]
	v_cvt_pk_bf16_f32 v54, v54, v55
	v_cvt_pk_bf16_f32 v55, v56, v57
	global_store_dwordx2 v[52:53], v[60:61], off
	global_store_dwordx2 v[52:53], v[54:55], off offset:1536
	v_mul_f32_e32 v52, 0x4b800000, v88
	v_cndmask_b32_e32 v52, v88, v52, vcc
	v_rsq_f32_e32 v52, v52
	s_nop 0
	v_mul_f32_e32 v53, 0x45800000, v52
	v_cndmask_b32_e32 v52, v52, v53, vcc
	v_pk_mul_f32 v[54:55], v[52:53], v[80:81] op_sel_hi:[0,1]
	v_pk_mul_f32 v[56:57], v[52:53], v[74:75] op_sel_hi:[0,1]
	v_pk_fma_f32 v[54:55], v[40:41], v[54:55], v[0:1]
	v_pk_fma_f32 v[56:57], v[36:37], v[56:57], v[2:3]
	v_cvt_pk_bf16_f32 v54, v54, v55
	v_cvt_pk_bf16_f32 v55, v56, v57
	global_store_dwordx2 v[58:59], v[54:55], off
	v_pk_mul_f32 v[54:55], v[52:53], v[76:77] op_sel_hi:[0,1]
	v_pk_mul_f32 v[56:57], v[52:53], v[70:71] op_sel_hi:[0,1]
	v_pk_fma_f32 v[54:55], v[42:43], v[54:55], v[4:5]
	v_pk_fma_f32 v[56:57], v[38:39], v[56:57], v[6:7]
	v_cvt_pk_bf16_f32 v54, v54, v55
	v_cvt_pk_bf16_f32 v55, v56, v57
	global_store_dwordx2 v[58:59], v[54:55], off offset:512
	v_pk_mul_f32 v[54:55], v[52:53], v[86:87] op_sel_hi:[0,1]
	v_pk_mul_f32 v[56:57], v[52:53], v[82:83] op_sel_hi:[0,1]
	v_pk_fma_f32 v[54:55], v[48:49], v[54:55], v[8:9]
	v_pk_fma_f32 v[56:57], v[44:45], v[56:57], v[10:11]
	v_cvt_pk_bf16_f32 v54, v54, v55
	v_cvt_pk_bf16_f32 v55, v56, v57
	global_store_dwordx2 v[58:59], v[54:55], off offset:1024
	v_pk_mul_f32 v[54:55], v[52:53], v[84:85] op_sel_hi:[0,1]
	v_pk_mul_f32 v[52:53], v[52:53], v[78:79] op_sel_hi:[0,1]
	v_pk_fma_f32 v[54:55], v[50:51], v[54:55], v[12:13]
	v_pk_fma_f32 v[52:53], v[46:47], v[52:53], v[14:15]
	v_cvt_pk_bf16_f32 v54, v54, v55
	v_cvt_pk_bf16_f32 v55, v52, v53
	global_store_dwordx2 v[58:59], v[54:55], off offset:1536
	v_and_b32_e32 v55, 0xffff0000, v32
	v_and_b32_e32 v57, 0xffff0000, v30
	v_lshlrev_b32_e32 v54, 16, v32
	v_lshlrev_b32_e32 v56, 16, v30
	v_mov_b32_e32 v62, v55
	v_mov_b32_e32 v63, v57
	v_lshlrev_b32_e32 v52, 16, v33
	v_and_b32_e32 v53, 0xffff0000, v33
	v_lshl_add_u64 v[32:33], v[34:35], 0, v[136:137]
	v_lshlrev_b32_e32 v34, 16, v31
	v_mov_b32_e32 v60, v54
	v_mov_b32_e32 v61, v56
	v_pk_mul_f32 v[62:63], v[62:63], v[62:63]
	v_and_b32_e32 v35, 0xffff0000, v31
	v_mov_b32_e32 v30, v52
	v_mov_b32_e32 v31, v34
	v_pk_fma_f32 v[60:61], v[60:61], v[60:61], v[62:63]
	v_and_b32_e32 v63, 0xffff0000, v26
	v_pk_fma_f32 v[30:31], v[30:31], v[30:31], v[60:61]
	v_and_b32_e32 v61, 0xffff0000, v28
	v_mov_b32_e32 v58, v53
	v_mov_b32_e32 v59, v35
	v_lshlrev_b32_e32 v60, 16, v28
	v_lshlrev_b32_e32 v62, 16, v26
	v_mov_b32_e32 v68, v63
	v_mov_b32_e32 v69, v61
	v_pk_fma_f32 v[30:31], v[58:59], v[58:59], v[30:31]
	v_lshlrev_b32_e32 v58, 16, v29
	v_lshlrev_b32_e32 v28, 16, v27
	v_mov_b32_e32 v66, v62
	v_mov_b32_e32 v67, v60
	v_pk_mul_f32 v[68:69], v[68:69], v[68:69]
	v_and_b32_e32 v59, 0xffff0000, v29
	v_and_b32_e32 v29, 0xffff0000, v27
	v_mov_b32_e32 v26, v28
	v_mov_b32_e32 v27, v58
	v_pk_fma_f32 v[66:67], v[66:67], v[66:67], v[68:69]
	v_and_b32_e32 v69, 0xffff0000, v20
	v_pk_fma_f32 v[26:27], v[26:27], v[26:27], v[66:67]
	v_and_b32_e32 v67, 0xffff0000, v22
	v_mov_b32_e32 v64, v29
	v_mov_b32_e32 v65, v59
	v_lshlrev_b32_e32 v66, 16, v22
	v_lshlrev_b32_e32 v68, 16, v20
	v_mov_b32_e32 v74, v67
	v_mov_b32_e32 v75, v69
	v_pk_fma_f32 v[26:27], v[64:65], v[64:65], v[26:27]
	v_lshlrev_b32_e32 v64, 16, v23
	v_and_b32_e32 v65, 0xffff0000, v23
	v_lshl_add_u64 v[22:23], v[24:25], 0, v[136:137]
	v_lshlrev_b32_e32 v24, 16, v21
	v_mov_b32_e32 v72, v66
	v_mov_b32_e32 v73, v68
	v_pk_mul_f32 v[74:75], v[74:75], v[74:75]
	v_and_b32_e32 v25, 0xffff0000, v21
	v_mov_b32_e32 v20, v64
	v_mov_b32_e32 v21, v24
	v_pk_fma_f32 v[72:73], v[72:73], v[72:73], v[74:75]
	v_and_b32_e32 v75, 0xffff0000, v16
	v_pk_fma_f32 v[20:21], v[20:21], v[20:21], v[72:73]
	v_and_b32_e32 v73, 0xffff0000, v18
	v_mov_b32_e32 v70, v65
	v_mov_b32_e32 v71, v25
	v_lshlrev_b32_e32 v72, 16, v18
	v_lshlrev_b32_e32 v74, 16, v16
	v_mov_b32_e32 v80, v73
	v_mov_b32_e32 v81, v75
	v_pk_fma_f32 v[20:21], v[70:71], v[70:71], v[20:21]
	v_lshlrev_b32_e32 v70, 16, v19
	v_lshlrev_b32_e32 v18, 16, v17
	v_mov_b32_e32 v78, v72
	v_mov_b32_e32 v79, v74
	v_pk_mul_f32 v[80:81], v[80:81], v[80:81]
	v_and_b32_e32 v71, 0xffff0000, v19
	v_and_b32_e32 v19, 0xffff0000, v17
	v_mov_b32_e32 v16, v70
	v_mov_b32_e32 v17, v18
	v_pk_fma_f32 v[78:79], v[78:79], v[78:79], v[80:81]
	v_mov_b32_e32 v76, v71
	v_mov_b32_e32 v77, v19
	v_pk_fma_f32 v[16:17], v[16:17], v[16:17], v[78:79]
	s_nop 0
	v_pk_fma_f32 v[16:17], v[76:77], v[76:77], v[16:17]
	v_mov_b32_e32 v76, v20
	v_mov_b32_e32 v77, v30
	v_mov_b32_e32 v30, v21
	v_pk_add_f32 v[20:21], v[76:77], v[30:31]
	v_mov_b32_e32 v30, v16
	v_mov_b32_e32 v31, v27
	v_pk_add_f32 v[20:21], v[20:21], v[30:31]
	v_pk_mov_b32 v[16:17], v[16:17], v[26:27] op_sel:[1,0]
	s_nop 0
	v_pk_add_f32 v[16:17], v[20:21], v[16:17]
	s_nop 1
	v_add_f32_dpp v16, v16, v16 row_ror:8 row_mask:0xf bank_mask:0xf
	v_add_f32_dpp v17, v17, v17 row_ror:8 row_mask:0xf bank_mask:0xf
	s_nop 0
	v_add_f32_dpp v16, v16, v16 row_ror:4 row_mask:0xf bank_mask:0xf
	v_add_f32_dpp v17, v17, v17 row_ror:4 row_mask:0xf bank_mask:0xf
	s_nop 0
	v_add_f32_dpp v16, v16, v16 row_ror:2 row_mask:0xf bank_mask:0xf
	v_add_f32_dpp v17, v17, v17 row_ror:2 row_mask:0xf bank_mask:0xf
	s_nop 0
	v_add_f32_dpp v16, v16, v16 row_ror:1 row_mask:0xf bank_mask:0xf
	v_add_f32_dpp v17, v17, v17 row_ror:1 row_mask:0xf bank_mask:0xf
	s_nop 0
	v_add_f32_dpp v16, v16, v16 row_bcast:15 row_mask:0xa bank_mask:0xf
	v_add_f32_dpp v17, v17, v17 row_bcast:15 row_mask:0xa bank_mask:0xf
	s_nop 0
	v_add_f32_dpp v16, v16, v16 row_bcast:31 row_mask:0xc bank_mask:0xf
	v_add_f32_dpp v17, v17, v17 row_bcast:31 row_mask:0xc bank_mask:0xf
	s_nop 0
	v_readlane_b32 s0, v16, 63
	v_readlane_b32 s1, v17, 63
	s_nop 1
	v_mov_b32_e32 v16, s0
	v_mov_b32_e32 v17, s1
	s_nop 0
	v_pk_fma_f32 v[16:17], v[16:17], s[20:21], v[96:97] op_sel_hi:[1,0,0]
	s_nop 0
	v_mul_f32_e32 v20, 0x4b800000, v17
	v_cmp_gt_f32_e64 s[0:1], s36, v17
	v_cmp_gt_f32_e32 vcc, s36, v16
	s_nop 0
	v_cndmask_b32_e64 v17, v17, v20, s[0:1]
	v_rsq_f32_e32 v17, v17
	s_nop 0
	v_mul_f32_e32 v20, 0x45800000, v17
	v_cndmask_b32_e64 v20, v17, v20, s[0:1]
	v_pk_mul_f32 v[26:27], v[20:21], v[54:55] op_sel_hi:[0,1]
	v_pk_mul_f32 v[30:31], v[20:21], v[52:53] op_sel_hi:[0,1]
	v_pk_fma_f32 v[26:27], v[40:41], v[26:27], v[0:1]
	v_pk_fma_f32 v[30:31], v[36:37], v[30:31], v[2:3]
	v_cvt_pk_bf16_f32 v26, v26, v27
	v_cvt_pk_bf16_f32 v27, v30, v31
	global_store_dwordx2 v[32:33], v[26:27], off
	v_pk_mul_f32 v[26:27], v[20:21], v[56:57] op_sel_hi:[0,1]
	v_pk_mul_f32 v[30:31], v[20:21], v[34:35] op_sel_hi:[0,1]
	v_mul_f32_e32 v17, 0x4b800000, v16
	v_pk_fma_f32 v[26:27], v[42:43], v[26:27], v[4:5]
	v_pk_fma_f32 v[30:31], v[38:39], v[30:31], v[6:7]
	v_cndmask_b32_e32 v16, v16, v17, vcc
	v_cvt_pk_bf16_f32 v26, v26, v27
	v_cvt_pk_bf16_f32 v27, v30, v31
	v_rsq_f32_e32 v16, v16
	global_store_dwordx2 v[32:33], v[26:27], off offset:512
	v_pk_mul_f32 v[26:27], v[20:21], v[60:61] op_sel_hi:[0,1]
	v_pk_mul_f32 v[30:31], v[20:21], v[58:59] op_sel_hi:[0,1]
	v_pk_fma_f32 v[26:27], v[48:49], v[26:27], v[8:9]
	v_pk_fma_f32 v[30:31], v[44:45], v[30:31], v[10:11]
	v_cvt_pk_bf16_f32 v26, v26, v27
	v_cvt_pk_bf16_f32 v27, v30, v31
	global_store_dwordx2 v[32:33], v[26:27], off offset:1024
	v_pk_mul_f32 v[26:27], v[20:21], v[62:63] op_sel_hi:[0,1]
	v_pk_mul_f32 v[20:21], v[20:21], v[28:29] op_sel_hi:[0,1]
	v_mul_f32_e32 v17, 0x45800000, v16
	v_pk_fma_f32 v[26:27], v[50:51], v[26:27], v[12:13]
	v_pk_fma_f32 v[20:21], v[46:47], v[20:21], v[14:15]
	v_cndmask_b32_e32 v16, v16, v17, vcc
	v_cvt_pk_bf16_f32 v26, v26, v27
	v_cvt_pk_bf16_f32 v27, v20, v21
	v_pk_mul_f32 v[20:21], v[16:17], v[66:67] op_sel_hi:[0,1]
	v_pk_fma_f32 v[0:1], v[40:41], v[20:21], v[0:1]
	v_pk_mul_f32 v[20:21], v[16:17], v[64:65] op_sel_hi:[0,1]
	v_pk_fma_f32 v[2:3], v[36:37], v[20:21], v[2:3]
	v_cvt_pk_bf16_f32 v0, v0, v1
	v_cvt_pk_bf16_f32 v1, v2, v3
	global_store_dwordx2 v[22:23], v[0:1], off
	v_pk_mul_f32 v[0:1], v[16:17], v[68:69] op_sel_hi:[0,1]
	v_pk_mul_f32 v[2:3], v[16:17], v[24:25] op_sel_hi:[0,1]
	v_pk_fma_f32 v[0:1], v[42:43], v[0:1], v[4:5]
	v_pk_fma_f32 v[2:3], v[38:39], v[2:3], v[6:7]
	v_cvt_pk_bf16_f32 v0, v0, v1
	v_cvt_pk_bf16_f32 v1, v2, v3
	global_store_dwordx2 v[22:23], v[0:1], off offset:512
	v_pk_mul_f32 v[0:1], v[16:17], v[72:73] op_sel_hi:[0,1]
	v_pk_mul_f32 v[2:3], v[16:17], v[70:71] op_sel_hi:[0,1]
	v_pk_fma_f32 v[0:1], v[48:49], v[0:1], v[8:9]
	v_pk_fma_f32 v[2:3], v[44:45], v[2:3], v[10:11]
	v_cvt_pk_bf16_f32 v0, v0, v1
	v_cvt_pk_bf16_f32 v1, v2, v3
	global_store_dwordx2 v[22:23], v[0:1], off offset:1024
	v_pk_mul_f32 v[0:1], v[16:17], v[74:75] op_sel_hi:[0,1]
	v_pk_mul_f32 v[2:3], v[16:17], v[18:19] op_sel_hi:[0,1]
	v_pk_fma_f32 v[0:1], v[50:51], v[0:1], v[12:13]
	v_pk_fma_f32 v[2:3], v[46:47], v[2:3], v[14:15]
	v_cvt_pk_bf16_f32 v0, v0, v1
	v_cvt_pk_bf16_f32 v1, v2, v3
	global_store_dwordx2 v[32:33], v[26:27], off offset:1536
	global_store_dwordx2 v[22:23], v[0:1], off offset:1536
	s_cbranch_scc0 .LBB0_135
